# FFN1-up tail: FFN2/PLE weight conversion split 7800/1608 items between the 21-unit and 22-unit halves of the grid so both finish together (on v32)
# baseline (speedup 1.0000x reference)
; #define LAS __attribute__((address_space(3)))
; template <int SET>
; __device__ __forceinline__ void transpose_set(const Args& a, LAS float* scr, int gw, int NGW, int lane) {
;     ...
;         constexpr int NITEMS = 2 * I_GU + I_DN + I_SQ + I_PL;
;         for (int it = gw; it < NITEMS; it += NGW) {
;             int r = it;
;             if (r < I_GU) { transpose_item(a.in[I_F2G], a.in[I_F2N], DM, FF, (bf16_t*)(ws + WS_GU2), 1, scr, r, lane); continue; } r -= I_GU;
;             if (r < I_GU) { transpose_item(a.in[I_F2U], a.in[I_F2N], DM, FF, (bf16_t*)(ws + WS_GU2), 2, scr, r, lane); continue; } r -= I_GU;
;             if (r < I_DN) { transpose_item(a.in[I_F2D], nullptr, FF, DM, (bf16_t*)(ws + WS_DN2), 0, scr, r, lane); continue; } r -= I_DN;
;             if (r < I_SQ) { transpose_item(a.in[I_WPG], a.in[I_PLN], DM, DM, (bf16_t*)(ws + WS_WPG), 0, scr, r, lane); continue; } r -= I_SQ;
;             transpose_item(a.in[I_WPLE], nullptr, PLE, DM, (bf16_t*)(ws + WS_WPLE), 0, scr, r, lane);
;         }
; __global__ void __launch_bounds__(512, 2) fwd_mega(Args a) {
;     ...
;     if (G == 256 && bx >= 128) {
;         transpose_set<1>(a, (LAS float*)(lds + wave * 16640), (bx - 128) * 8 + wave, 1024, lane); __syncthreads(); }
.LBB0_252:
	s_cmpk_gt_i32 s2, 0x7f
	s_cselect_b64 s[0:1], -1, 0
	v_writelane_b32 v251, s0, 44
	s_nop 1
	v_writelane_b32 v251, s1, 45
	s_nop 0
	v_readlane_b32 s4, v251, 34
	v_readlane_b32 s5, v251, 35
	s_and_b64 vcc, exec, s[4:5]
	s_cbranch_vccz .LBB0_369
	s_cmpk_gt_i32 s2, 0x7f
	s_cbranch_scc1 .Ltt_hi
	s_add_i32 s18, s96, 0x1e78
	s_movk_i32 s98, 0x24bf
	s_movk_i32 s99, 0x20c0
	s_branch .Ltt_go
.Ltt_hi:
	s_add_i32 s18, s96, 0xfffffc00
	s_movk_i32 s98, 0x1e77
	s_movk_i32 s99, 0x1a78
.Ltt_go:
	s_cmp_gt_i32 s18, s98
	s_cbranch_scc1 .LBB0_368
	v_lshlrev_b32_e32 v1, 3, v204
	v_lshrrev_b32_e32 v96, 3, v228
	v_and_b32_e32 v1, 56, v1
	v_lshrrev_b32_e32 v68, 4, v228
	v_mul_u32_u24_e32 v4, 0x104, v1
	v_lshlrev_b32_e32 v70, 1, v1
	v_lshlrev_b32_e32 v1, 2, v96
	s_movk_i32 s4, 0x104
	v_mov_b32_e32 v71, 0
	v_add3_u32 v97, s34, v4, v1
	v_or_b32_e32 v1, 4, v68
	v_mov_b32_e32 v4, 0x410
	v_lshl_add_u64 v[2:3], s[92:93], 0, v[70:71]
	s_mov_b64 s[0:1], 0xa200000
	v_mad_u32_u24 v106, v1, s4, v4
	v_mov_b32_e32 v4, 0xc30
	v_and_b32_e32 v0, 15, v204
	v_lshl_add_u64 v[72:73], v[2:3], 0, s[0:1]
	v_mad_u32_u24 v107, v1, s4, v4
	v_mov_b32_e32 v4, 0x1450
	s_mov_b64 s[0:1], 0x9a00000
	v_readlane_b32 s52, v251, 1
	v_lshlrev_b32_e32 v0, 4, v0
	v_mad_u32_u24 v108, v1, s4, v4
	v_mov_b32_e32 v4, 0x1c70
	v_lshl_add_u64 v[74:75], v[2:3], 0, s[0:1]
	s_mov_b64 s[0:1], 0x6c00000
	v_readlane_b32 s62, v251, 11
	v_readlane_b32 s63, v251, 12
	s_cmp_lg_u64 s[38:39], 0
	v_add_u32_e32 v94, s34, v0
	v_mad_u32_u24 v109, v1, s4, v4
	v_mov_b32_e32 v4, 0x2490
	v_lshl_add_u64 v[76:77], v[2:3], 0, s[0:1]
	s_mov_b64 s[0:1], 0x4100000
	s_cselect_b64 s[6:7], -1, 0
	s_cmp_lg_u64 s[62:63], 0
	v_mad_u32_u24 v95, v68, s4, v94
	v_mul_u32_u24_e32 v105, 0x104, v1
	v_mad_u32_u24 v110, v1, s4, v4
	v_lshl_add_u64 v[78:79], v[2:3], 0, s[0:1]
	v_mov_b32_e32 v1, v71
	v_readlane_b32 s64, v251, 13
	v_readlane_b32 s65, v251, 14
	v_readlane_b32 s66, v251, 15
	v_readlane_b32 s67, v251, 16
	s_cselect_b64 s[8:9], -1, 0
	s_lshl_b32 s0, s18, 1
	v_or_b32_e32 v98, 8, v96
	v_or_b32_e32 v99, 16, v96
	v_or_b32_e32 v100, 24, v96
	v_or_b32_e32 v101, 32, v96
	v_or_b32_e32 v102, 40, v96
	v_or_b32_e32 v103, 48, v96
	v_or_b32_e32 v104, 56, v96
	v_lshl_add_u64 v[80:81], s[42:43], 0, v[0:1]
	v_lshl_add_u64 v[82:83], s[40:41], 0, v[0:1]
	v_lshl_add_u64 v[84:85], s[36:37], 0, v[0:1]
	v_lshl_add_u64 v[86:87], s[66:67], 0, v[0:1]
	v_lshl_add_u64 v[88:89], s[64:65], 0, v[0:1]
	v_mov_b32_e32 v69, v71
	s_lshl_b32 s19, s18, 6
	s_lshl_b32 s20, s18, 7
	s_add_i32 s21, s0, 0x1d500
	s_mov_b32 s11, 0
	s_mov_b32 s22, 0x40000
	v_add_u32_e32 v111, 0x410, v95
	v_add_u32_e32 v112, 0x418, v95
	v_add_u32_e32 v113, 0x820, v95
	v_add_u32_e32 v114, 0x828, v95
	v_add_u32_e32 v115, 0xc30, v95
	v_add_u32_e32 v116, 0xc38, v95
	v_add_u32_e32 v117, 0x1040, v95
	v_add_u32_e32 v118, 0x1048, v95
	v_add_u32_e32 v119, 0x1450, v95
	v_add_u32_e32 v120, 0x1458, v95
	v_add_u32_e32 v121, 0x1860, v95
	v_add_u32_e32 v122, 0x1868, v95
	v_add_u32_e32 v123, 0x1c70, v95
	s_movk_i32 s23, 0x7fff
	s_mov_b32 s24, 0xffff0000
	s_movk_i32 s25, 0x5600
	s_mov_b32 s26, 0x15000
	s_mov_b32 s27, 0x2b000
	s_mov_b32 s30, 0x56000
	s_mov_b32 s31, 0x6b000
	s_mov_b32 s34, 0x81000
	s_mov_b32 s35, 0x96000
	s_mov_b32 s36, 0xac000
	s_mov_b32 s37, 0xc1000
	s_mov_b32 s40, 0xd7000
	s_mov_b32 s41, 0xec000
	s_mov_b32 s42, 0x102000
	v_add_u32_e32 v124, 0x1c78, v95
	v_add_u32_e32 v125, 0x2080, v95
	v_readlane_b32 s53, v251, 2
	v_readlane_b32 s54, v251, 3
	v_readlane_b32 s55, v251, 4
	v_readlane_b32 s56, v251, 5
	v_readlane_b32 s57, v251, 6
	v_readlane_b32 s58, v251, 7
	v_readlane_b32 s59, v251, 8
	v_readlane_b32 s60, v251, 9
	v_readlane_b32 s61, v251, 10
	s_branch .LBB0_258

; template <int SET>
; __device__ __forceinline__ void transpose_set(const Args& a, LAS float* scr, int gw, int NGW, int lane) {
;     ...
;         for (int it = gw; it < NITEMS; it += NGW) {
;             int r = it;
;             if (r < I_GU) { transpose_item(a.in[I_F2G], a.in[I_F2N], DM, FF, (bf16_t*)(ws + WS_GU2), 1, scr, r, lane); continue; } r -= I_GU;
;             if (r < I_GU) { transpose_item(a.in[I_F2U], a.in[I_F2N], DM, FF, (bf16_t*)(ws + WS_GU2), 2, scr, r, lane); continue; } r -= I_GU;
;             if (r < I_DN) { transpose_item(a.in[I_F2D], nullptr, FF, DM, (bf16_t*)(ws + WS_DN2), 0, scr, r, lane); continue; } r -= I_DN;
;             if (r < I_SQ) { transpose_item(a.in[I_WPG], a.in[I_PLN], DM, DM, (bf16_t*)(ws + WS_WPG), 0, scr, r, lane); continue; } r -= I_SQ;
;             transpose_item(a.in[I_WPLE], nullptr, PLE, DM, (bf16_t*)(ws + WS_WPLE), 0, scr, r, lane);
;         }
.LBB0_257:
	s_add_i32 s0, s18, 0x400
	s_add_i32 s19, s19, 0x10000
	s_add_i32 s20, s20, 0x20000
	s_addk_i32 s21, 0x800
	s_cmp_lt_i32 s18, s99
	s_mov_b32 s18, s0
	s_cbranch_scc0 .LBB0_368
